# P2b queue: diff units popped before sb units within each query-block group (bit 5 of unit index flipped); on top of v58
# baseline (speedup 1.0000x reference)
.LBB0_349:
	v_readlane_b32 s0, v255, 16
	s_waitcnt lgkmcnt(0)
	s_barrier
	v_mov_b32_e32 v0, s0
	ds_read_b32 v0, v0
	s_movk_i32 s0, 0x4ff
	s_waitcnt lgkmcnt(0)
	s_barrier
	v_cmp_lt_u32_e32 vcc, s0, v0
	v_readfirstlane_b32 s16, v0
	s_mov_b64 s[0:1], -1
	s_cbranch_vccnz .LBB0_342
	s_cmpk_gt_u32 s16, 0x3ff
	s_cbranch_scc1 .Lq_df_done
	s_xor_b32 s16, s16, 32
